# GEMM phase prologue: all 14 staging DMAs issued before the first counted wait (on top of the attention stack)
# baseline (speedup 1.0000x reference)
; DI int tid_opaque() { int t = threadIdx.x; asm volatile("" : "+v"(t)); return t; }
; #define PG8_STAGE(bufoff, gbase, ld) do { if ((bufoff) >= 4 * HTB) PG8_STAGE_(sRb, bufoff, gbase, ld); else PG8_STAGE_(sR, bufoff, gbase, ld); } while (0)
; #define PG8_WAIT_V(n) asm volatile("s_waitcnt vmcnt(" #n ")" ::: "memory")
; #define PG8_BAR __builtin_amdgcn_s_barrier()
; DI void gemm_phase(LAS unsigned char* lds, const Sched& S_, const Epi& E) {
;     ...
;     const int tid = tid_opaque(), wid = __builtin_amdgcn_readfirstlane(tid >> 6), lane = tid & 63, wr = wid >> 2, wc = wid & 3, fr = lane & 15, fq = lane >> 4;
;     int sR[2], sRb[2], sC[2];
; #pragma unroll
;     for (int i = 0; i < 2; ++i) { int R, C; stage_rc(tid * 16 + i * 8192, R, C); sR[i] = R; sRb[i] = (R & ~31) + perm32(R & 31); sC[i] = C * 2; }
;     const size_t kstep = (size_t)(BK * 2);
;     const unsigned ldsw = (unsigned)wid * 1024u;
;     const int aoff = lds_byte(wr * 64 + fr, fq * 8), boff = lds_byte(wc * 32 + fr, fq * 8);
;     ...
;     {
;         const size_t hA = (size_t)HALF * clda, hB = (size_t)HALF * cldb;
;         PG8_STAGE(PG8_SB(0, 0), cB, cldb); PG8_STAGE(PG8_SB(0, 1), cB + hB, cldb); PG8_STAGE(PG8_SA(0, 0), cA, clda); PG8_STAGE(PG8_SA(0, 1), cA + hA, clda);
;         if (wr == 1) PG8_BAR;
;         PG8_WAIT_V(2); PG8_BAR;
;         PG8_STAGE(PG8_SB(1, 0), cB + kstep, cldb); PG8_STAGE(PG8_SA(1, 0), cA + kstep, clda); PG8_STAGE(PG8_SB(1, 1), cB + hB + kstep, cldb);
;         PG8_WAIT_V(6); PG8_BAR;
;     }
.LBB0_282:
	s_add_i32 m0, s31, 0x18000
	v_lshl_add_u64 v[2:3], v[2:3], 0, s[34:35]
	global_load_lds_dwordx4 v[2:3], off
	v_lshl_add_u64 v[2:3], v[4:5], 0, s[34:35]
	s_add_i32 m0, s31, 0x1a000
	s_add_i32 s25, s31, 0x8000
	global_load_lds_dwordx4 v[2:3], off
	v_lshl_add_u64 v[2:3], v[10:11], 0, s[34:35]
	s_mov_b32 m0, s25
	s_add_i32 s26, s31, 0xa000
	global_load_lds_dwordx4 v[2:3], off
	v_lshl_add_u64 v[2:3], v[12:13], 0, s[34:35]
	s_mov_b32 m0, s26
	v_bfe_u32 v224, v169, 4, 2
	global_load_lds_dwordx4 v[2:3], off
	s_add_i32 m0, s31, 0x1c000
	v_lshl_add_u64 v[2:3], v[6:7], 0, s[34:35]
	global_load_lds_dwordx4 v[2:3], off
	v_lshl_add_u64 v[2:3], v[8:9], 0, s[34:35]
	s_add_i32 m0, s31, 0x1e000
	v_and_b32_e32 v223, 15, v169
	global_load_lds_dwordx4 v[2:3], off
	s_waitcnt vmcnt(8)
	s_barrier
	v_lshlrev_b32_e32 v17, 4, v224
	v_lshlrev_b32_e32 v18, 2, v169
	s_and_b32 s13, s4, 3
	v_lshl_or_b32 v17, v223, 6, v17
	s_lshl_b32 s4, s5, 13
	v_and_b32_e32 v18, 32, v18
	s_lshl_b32 s9, s5, 6
	v_bitop3_b32 v19, v17, s4, v18 bitop3:0xde
	s_lshl_b32 s24, s13, 5
	s_lshl_b32 s4, s13, 12
	s_ashr_i32 s27, s65, 31
	v_bitop3_b32 v225, v17, s4, v18 bitop3:0xde
	s_waitcnt lgkmcnt(0)
	s_add_u32 s4, s52, 0x3800000
	v_writelane_b32 v252, s4, 13
	s_addc_u32 s4, s53, 0
	v_writelane_b32 v252, s4, 14
	s_add_u32 s4, s52, 0x2600000
	v_writelane_b32 v252, s4, 15
	s_addc_u32 s4, s53, 0
	v_writelane_b32 v252, s4, 16
	s_add_u32 s4, s52, 0x1aa00000
	v_writelane_b32 v252, s4, 17
	s_addc_u32 s4, s53, 0
	v_writelane_b32 v252, s4, 18
	s_add_u32 s4, s52, 0x2400000
	v_writelane_b32 v252, s4, 19
	s_addc_u32 s4, s53, 0
	v_writelane_b32 v252, s4, 20
	s_add_u32 s4, s52, 0x1000000
	v_writelane_b32 v252, s4, 21
	s_addc_u32 s4, s53, 0
	v_writelane_b32 v252, s4, 22
	s_add_u32 s4, s52, 0x2100000
	v_writelane_b32 v252, s4, 23
	s_addc_u32 s4, s53, 0
	v_writelane_b32 v252, s4, 24
	s_add_u32 s4, s52, 0xa800000
	v_writelane_b32 v252, s4, 25
	s_addc_u32 s4, s53, 0
	v_writelane_b32 v252, s4, 26
	s_add_u32 s4, s52, 0x2080000
	v_writelane_b32 v252, s4, 27
	s_addc_u32 s4, s53, 0
	v_writelane_b32 v252, s4, 28
	s_add_u32 s4, s52, 0x7800000
	v_writelane_b32 v252, s4, 29
	s_addc_u32 s4, s53, 0
	v_writelane_b32 v252, s4, 30
	s_add_u32 s4, s52, 0x1f00000
	v_writelane_b32 v252, s4, 31
	s_addc_u32 s4, s53, 0
	v_writelane_b32 v252, s4, 32
	s_add_u32 s4, s52, 0xba00000
	v_writelane_b32 v252, s4, 33
	s_addc_u32 s4, s53, 0
	v_writelane_b32 v252, s4, 34
	s_add_u32 s4, s52, 0x2e00000
	v_writelane_b32 v252, s4, 35
	s_addc_u32 s4, s53, 0
	s_cmpk_lt_u32 s2, 0x100
	s_cselect_b64 s[20:21], -1, 0
	s_cmp_lt_u32 s40, 8
	v_writelane_b32 v252, s4, 36
	s_cselect_b64 s[16:17], -1, 0
	s_ashr_i32 s73, s72, 31
	v_writelane_b32 v252, s40, 37
	s_lshl_b64 s[18:19], s[72:73], 17
	v_writelane_b32 v252, s18, 38
	s_lshl_b32 s42, s72, 10
	s_lshl_b64 s[4:5], s[72:73], 21
	v_writelane_b32 v252, s19, 39
	s_add_i32 s18, s72, 1
	s_lshr_b32 s14, s18, 31
	s_add_i32 s14, s18, s14
	s_and_b32 s14, s14, -2
	s_sub_i32 s14, s18, s14
	s_mul_i32 s28, s14, 0xc000
	s_lshl_b32 s38, s14, 10
	s_ashr_i32 s19, s18, 31
	s_ashr_i32 s29, s28, 31
	s_ashr_i32 s39, s38, 31
	s_ashr_i32 s43, s42, 31
	s_lshl_b64 s[18:19], s[18:19], 21
	v_writelane_b32 v252, s18, 40
	s_cmp_lg_u32 s72, 1
	s_waitcnt vmcnt(6)
	v_and_b32_e32 v0, 1, v0
	v_writelane_b32 v252, s19, 41
	s_cselect_b64 s[18:19], -1, 0
	v_writelane_b32 v252, s18, 42
	s_bitcmp0_b32 s2, 6
	v_lshlrev_b32_e32 v2, 1, v14
	v_writelane_b32 v252, s19, 43
	s_cselect_b64 s[18:19], -1, 0
	v_writelane_b32 v252, s18, 44
	s_cmp_eq_u32 s13, 0
	v_lshl_add_u32 v226, v0, 6, v2
	v_writelane_b32 v252, s19, 45
	s_cselect_b64 s[18:19], -1, 0
	v_writelane_b32 v252, s18, 46
	v_and_b32_e32 v0, 1, v15
	v_lshlrev_b32_e32 v2, 1, v16
	v_writelane_b32 v252, s19, 47
	s_lshl_b64 s[18:19], s[28:29], 2
	v_writelane_b32 v252, s18, 48
	s_mov_b32 s73, 0
	v_lshl_add_u32 v227, v0, 6, v2
	v_writelane_b32 v252, s19, 49
	s_lshl_b64 s[18:19], s[38:39], 2
	v_writelane_b32 v252, s18, 50
	v_add_u32_e32 v228, 0, v19
	s_mov_b32 s39, s68
	v_writelane_b32 v252, s19, 51
	s_lshl_b64 s[18:19], s[42:43], 2
	v_writelane_b32 v252, s18, 52
	s_barrier
	s_nop 0
	v_writelane_b32 v252, s19, 53
	s_branch .LBB0_285
